# plus: removed NaN-canonicalising v_max before each relu in the indexer score loops (MFMA results cannot be sNaN); s_nop added where an MFMA-result read got closer
# speedup vs baseline: 1.0715x; 1.0114x over previous
; #define LAS __attribute__((address_space(3)))
; template <int MODE> __device__ __forceinline__ void indexer_pair(LAS unsigned char* lds, const GAS f16* KI, int b, int t0, int ntiles, int tile, int n, int g,
;         const h8 (&A)[2][4], const float (&w)[2][2][8], const h8 (&BA)[4], const h8 (&BB)[4], h8 (&NA)[4], h8 (&NB)[4]) {
;     ...
;         for (int mt = 0; mt < 2; ++mt) { cA[mt] = __builtin_amdgcn_mfma_f32_32x32x16_f16(A[mt][0], BA[0], f32x16{}, 0, 0, 0); cB[mt] = __builtin_amdgcn_mfma_f32_32x32x16_f16(A[mt][0], BB[0], f32x16{}, 0, 0, 0); }
; #pragma unroll
;         for (int kk = 1; kk < 4; ++kk)
; #pragma unroll
;             for (int mt = 0; mt < 2; ++mt) { cA[mt] = __builtin_amdgcn_mfma_f32_32x32x16_f16(A[mt][kk], BA[kk], cA[mt], 0, 0, 0); cB[mt] = __builtin_amdgcn_mfma_f32_32x32x16_f16(A[mt][kk], BB[kk], cB[mt], 0, 0, 0); }
; #pragma unroll
;         for (int u = 0; u < 2; ++u) {
;             const int s = (tile + u * NW) * 32 + n;
;             if (u == 0 || hasB) {
; #pragma unroll
;                 for (int mt = 0; mt < 2; ++mt)
; #pragma unroll
;                     for (int qq = 0; qq < 2; ++qq) {
;                         float sc = 0.f;
; #pragma unroll
;                         for (int h = 0; h < 8; ++h) sc += w[mt][qq][h] * fmaxf(u ? cB[mt][8 * qq + h] : cA[mt][8 * qq + h], 0.f);
;                         const int ql = 4 * mt + 2 * g + qq;
;                         int key = (int)(sc * 4096.f + 32768.5f);
;                         key = key < 1 ? 1 : (key > 65535 ? 65535 : key);
;                         if (s > t0 + ql) key = 0;
;                         KS[ql * SEQ + s] = (unsigned short)key;
;                         __hip_atomic_fetch_add((LAS unsigned*)(lds + 131072) + ql * 256 + (key >> 8), 1u, __ATOMIC_RELAXED, __HIP_MEMORY_SCOPE_WORKGROUP);
.LBB0_365:
	s_waitcnt vmcnt(3)
	v_mfma_f32_32x32x16_f16 v[28:43], v[60:63], v[140:143], 0
	s_add_i32 s27, s25, 16
	s_cmp_lt_u32 s27, s22
	s_cselect_b64 s[20:21], -1, 0
	s_and_b64 s[52:53], s[20:21], exec
	s_cselect_b32 s36, s27, s25
	s_add_i32 s37, s25, 24
	s_cmp_lt_u32 s37, s22
	s_waitcnt vmcnt(2)
	v_mfma_f32_32x32x16_f16 v[28:43], v[64:67], v[144:147], v[28:43]
	s_cselect_b32 s37, s37, s36
	v_lshl_add_u32 v0, s36, 5, v233
	v_ashrrev_i32_e32 v1, 31, v0
	v_lshl_add_u32 v2, s37, 5, v233
	v_lshlrev_b64 v[0:1], 7, v[0:1]
	v_ashrrev_i32_e32 v3, 31, v2
	v_lshl_add_u64 v[0:1], v[202:203], 0, v[0:1]
	s_waitcnt vmcnt(1)
	v_mfma_f32_32x32x16_f16 v[28:43], v[68:71], v[148:151], v[28:43]
	v_lshlrev_b64 v[2:3], 7, v[2:3]
	s_waitcnt vmcnt(0)
	v_lshl_add_u64 v[156:157], v[202:203], 0, v[2:3]
	global_load_dwordx4 v[184:187], v[0:1], off
	global_load_dwordx4 v[172:175], v[0:1], off offset:1024
	global_load_dwordx4 v[176:179], v[156:157], off
	global_load_dwordx4 v[168:171], v[156:157], off offset:1024
	global_load_dwordx4 v[164:167], v[0:1], off offset:2048
	global_load_dwordx4 v[160:163], v[0:1], off offset:3072
	global_load_dwordx4 v[180:183], v[156:157], off offset:2048
	s_nop 0
	global_load_dwordx4 v[156:159], v[156:157], off offset:3072
	v_cmp_le_i32_e32 vcc, v239, v234
	s_cmp_ge_i32 s25, s23
	s_waitcnt vmcnt(8)
	v_mfma_f32_32x32x16_f16 v[28:43], v[72:75], v[152:155], v[28:43]
	v_mfma_f32_32x32x16_f16 v[44:59], v[92:95], v[140:143], 0
	s_nop 10
	v_max_f32_e32 v0, 0, v28
	v_max_f32_e32 v1, 0, v29
	v_max_f32_e32 v2, 0, v30
	v_fma_f32 v0, v76, v0, 0
	v_max_f32_e32 v3, 0, v31
	v_fmac_f32_e32 v0, v77, v1
	v_fmac_f32_e32 v0, v78, v2
	v_max_f32_e32 v1, 0, v32
	v_fmac_f32_e32 v0, v79, v3
	v_fmac_f32_e32 v0, v80, v1
	v_max_f32_e32 v1, 0, v33
	v_fmac_f32_e32 v0, v81, v1
	v_max_f32_e32 v1, 0, v34
	v_fmac_f32_e32 v0, v82, v1
	v_max_f32_e32 v1, 0, v35
	v_fmac_f32_e32 v0, v83, v1
	v_fmamk_f32 v0, v0, 0x45800000, v226
	v_cvt_i32_f32_e32 v32, v0
	v_add_u32_e32 v33, 0xffff0000, v238
	v_mfma_f32_32x32x16_f16 v[44:59], v[96:99], v[144:147], v[44:59]
	v_max_f32_e32 v34, 0, v37
	v_med3_i32 v32, v32, 1, s33
	v_cndmask_b32_e32 v32, 0, v32, vcc
	ds_write_b16 v33, v32
	v_max_f32_e32 v33, 0, v36
	v_fma_f32 v33, v84, v33, 0
	v_fmac_f32_e32 v33, v85, v34
	v_max_f32_e32 v34, 0, v38
	v_fmac_f32_e32 v33, v86, v34
	v_max_f32_e32 v34, 0, v39
	v_fmac_f32_e32 v33, v87, v34
	v_max_f32_e32 v34, 0, v40
	v_mfma_f32_32x32x16_f16 v[44:59], v[100:103], v[148:151], v[44:59]
	v_fmac_f32_e32 v33, v88, v34
	v_max_f32_e32 v34, 0, v41
	v_fmac_f32_e32 v33, v89, v34
	v_max_f32_e32 v34, 0, v42
	v_fmac_f32_e32 v33, v90, v34
	v_max_f32_e32 v34, 0, v43
	v_fmac_f32_e32 v33, v91, v34
	v_mfma_f32_32x32x16_f16 v[44:59], v[104:107], v[152:155], v[44:59]
	v_fmamk_f32 v33, v33, 0x45800000, v226
	v_cvt_i32_f32_e32 v33, v33
	v_bfe_u32 v32, v32, 8, 8
	v_lshl_add_u32 v32, v32, 2, v212
	ds_add_u32 v32, v227
	v_med3_i32 v32, v33, 1, s33
	v_cmp_le_i32_e32 vcc, v239, v235
	v_add_u32_e32 v33, 0xffff4000, v238
	s_nop 3
	v_max_f32_e32 v34, 0, v45
	v_cndmask_b32_e32 v32, 0, v32, vcc
	ds_write_b16 v33, v32
	v_max_f32_e32 v33, 0, v44
	v_fma_f32 v33, v108, v33, 0
	v_fmac_f32_e32 v33, v109, v34
	v_max_f32_e32 v34, 0, v46
	v_fmac_f32_e32 v33, v110, v34
	v_max_f32_e32 v34, 0, v47
	v_fmac_f32_e32 v33, v111, v34
	v_max_f32_e32 v34, 0, v48
	v_fmac_f32_e32 v33, v112, v34
	v_max_f32_e32 v34, 0, v49
	v_fmac_f32_e32 v33, v113, v34
	v_max_f32_e32 v34, 0, v50
	v_fmac_f32_e32 v33, v114, v34
	v_max_f32_e32 v34, 0, v51
	v_fmac_f32_e32 v33, v115, v34
	v_fmamk_f32 v33, v33, 0x45800000, v226
	v_cvt_i32_f32_e32 v33, v33
	v_mfma_f32_32x32x16_f16 v[16:31], v[60:63], v[124:127], 0
	v_bfe_u32 v32, v32, 8, 8
	v_lshl_add_u32 v32, v32, 2, v214
	ds_add_u32 v32, v227
	v_med3_i32 v32, v33, 1, s33
	v_max_f32_e32 v33, 0, v52
	v_max_f32_e32 v34, 0, v53
	v_mfma_f32_32x32x16_f16 v[0:15], v[92:95], v[124:127], 0
	v_fma_f32 v33, v116, v33, 0
	v_fmac_f32_e32 v33, v117, v34
	v_max_f32_e32 v34, 0, v54
	v_fmac_f32_e32 v33, v118, v34
	v_max_f32_e32 v34, 0, v55
	v_mfma_f32_32x32x16_f16 v[16:31], v[64:67], v[128:131], v[16:31]
	v_fmac_f32_e32 v33, v119, v34
	v_max_f32_e32 v34, 0, v56
	v_fmac_f32_e32 v33, v120, v34
	v_max_f32_e32 v34, 0, v57
	v_mfma_f32_32x32x16_f16 v[0:15], v[96:99], v[128:131], v[0:15]
	v_fmac_f32_e32 v33, v121, v34
	v_max_f32_e32 v34, 0, v58
	v_fmac_f32_e32 v33, v122, v34
	v_max_f32_e32 v34, 0, v59
	v_fmac_f32_e32 v33, v123, v34
	v_mfma_f32_32x32x16_f16 v[16:31], v[68:71], v[132:135], v[16:31]
	v_fmamk_f32 v33, v33, 0x45800000, v226
	v_cmp_le_i32_e32 vcc, v239, v236
	v_cvt_i32_f32_e32 v33, v33
	s_nop 0
	v_cndmask_b32_e32 v32, 0, v32, vcc
	ds_write_b16 v238, v32
	v_bfe_u32 v32, v32, 8, 8
	v_mfma_f32_32x32x16_f16 v[0:15], v[100:103], v[132:135], v[0:15]
	v_lshl_add_u32 v32, v32, 2, v216
	ds_add_u32 v32, v227
	v_med3_i32 v32, v33, 1, s33
	v_cmp_le_i32_e32 vcc, v239, v237
	s_nop 1
	v_cndmask_b32_e32 v32, 0, v32, vcc
	v_mfma_f32_32x32x16_f16 v[16:31], v[72:75], v[136:139], v[16:31]
	ds_write_b16 v238, v32 offset:16384
	v_bfe_u32 v32, v32, 8, 8
	v_lshl_add_u32 v32, v32, 2, v218
	ds_add_u32 v32, v227
	v_mfma_f32_32x32x16_f16 v[0:15], v[104:107], v[136:139], v[0:15]
	s_cbranch_scc1 .LBB0_367
; #define LAS __attribute__((address_space(3)))
; template <int MODE> __device__ __forceinline__ void indexer_pair(LAS unsigned char* lds, const GAS f16* KI, int b, int t0, int ntiles, int tile, int n, int g,
;         const h8 (&A)[2][4], const float (&w)[2][2][8], const h8 (&BA)[4], const h8 (&BB)[4], h8 (&NA)[4], h8 (&NB)[4]) {
;     ...
; #pragma unroll
;         for (int u = 0; u < 2; ++u) {
;             const int s = (tile + u * NW) * 32 + n;
;             if (u == 0 || hasB) {
; #pragma unroll
;                 for (int mt = 0; mt < 2; ++mt)
; #pragma unroll
;                     for (int qq = 0; qq < 2; ++qq) {
;                         float sc = 0.f;
; #pragma unroll
;                         for (int h = 0; h < 8; ++h) sc += w[mt][qq][h] * fmaxf(u ? cB[mt][8 * qq + h] : cA[mt][8 * qq + h], 0.f);
;                         const int ql = 4 * mt + 2 * g + qq;
;                         int key = (int)(sc * 4096.f + 32768.5f);
;                         key = key < 1 ? 1 : (key > 65535 ? 65535 : key);
;                         if (s > t0 + ql) key = 0;
;                         KS[ql * SEQ + s] = (unsigned short)key;
;                         __hip_atomic_fetch_add((LAS unsigned*)(lds + 131072) + ql * 256 + (key >> 8), 1u, __ATOMIC_RELAXED, __HIP_MEMORY_SCOPE_WORKGROUP);
;                     }
;             }
;         }
	s_nop 5
	v_max_f32_e32 v16, 0, v16
	v_max_f32_e32 v17, 0, v17
	v_fma_f32 v16, v76, v16, 0
	v_fmac_f32_e32 v16, v77, v17
	v_max_f32_e32 v17, 0, v18
	v_fmac_f32_e32 v16, v78, v17
	v_max_f32_e32 v17, 0, v19
	v_fmac_f32_e32 v16, v79, v17
	v_max_f32_e32 v17, 0, v20
	v_fmac_f32_e32 v16, v80, v17
	v_max_f32_e32 v17, 0, v21
	v_fmac_f32_e32 v16, v81, v17
	v_max_f32_e32 v17, 0, v22
	v_fmac_f32_e32 v16, v82, v17
	v_max_f32_e32 v17, 0, v23
	v_fmac_f32_e32 v16, v83, v17
	v_fmamk_f32 v16, v16, 0x45800000, v226
	v_cvt_i32_f32_e32 v16, v16
	v_add_u32_e32 v17, 0x100, v239
	v_cmp_le_i32_e32 vcc, v17, v234
	v_add_u32_e32 v18, 0xffff0200, v238
	v_med3_i32 v16, v16, 1, s33
	v_cndmask_b32_e32 v16, 0, v16, vcc
	ds_write_b16 v18, v16
	v_max_f32_e32 v18, 0, v24
	v_max_f32_e32 v19, 0, v25
	v_fma_f32 v18, v84, v18, 0
	v_fmac_f32_e32 v18, v85, v19
	v_max_f32_e32 v19, 0, v26
	v_fmac_f32_e32 v18, v86, v19
	v_max_f32_e32 v19, 0, v27
	v_fmac_f32_e32 v18, v87, v19
	v_max_f32_e32 v19, 0, v28
	v_max_f32_e32 v0, 0, v0
	v_fmac_f32_e32 v18, v88, v19
	v_max_f32_e32 v19, 0, v29
	v_max_f32_e32 v1, 0, v1
	v_fma_f32 v0, v108, v0, 0
	v_fmac_f32_e32 v18, v89, v19
	v_max_f32_e32 v19, 0, v30
	v_fmac_f32_e32 v0, v109, v1
	v_max_f32_e32 v1, 0, v2
	v_fmac_f32_e32 v18, v90, v19
	v_max_f32_e32 v19, 0, v31
	v_fmac_f32_e32 v0, v110, v1
	v_max_f32_e32 v1, 0, v3
	v_fmac_f32_e32 v18, v91, v19
	v_fmac_f32_e32 v0, v111, v1
	v_max_f32_e32 v1, 0, v4
	v_fmamk_f32 v18, v18, 0x45800000, v226
	v_cvt_i32_f32_e32 v18, v18
	v_fmac_f32_e32 v0, v112, v1
	v_max_f32_e32 v1, 0, v5
	v_bfe_u32 v16, v16, 8, 8
	v_fmac_f32_e32 v0, v113, v1
	v_max_f32_e32 v1, 0, v6
	v_lshl_add_u32 v16, v16, 2, v212
	ds_add_u32 v16, v227
	v_med3_i32 v16, v18, 1, s33
	v_cmp_le_i32_e32 vcc, v17, v235
	v_fmac_f32_e32 v0, v114, v1
	v_max_f32_e32 v1, 0, v7
	v_cndmask_b32_e32 v16, 0, v16, vcc
	v_add_u32_e32 v18, 0xffff4200, v238
	v_fmac_f32_e32 v0, v115, v1
	v_bfe_u32 v1, v16, 8, 8
	ds_write_b16 v18, v16
	v_lshl_add_u32 v1, v1, 2, v214
	ds_add_u32 v1, v227
	v_max_f32_e32 v1, 0, v8
	v_max_f32_e32 v2, 0, v9
	v_fma_f32 v1, v116, v1, 0
	v_fmac_f32_e32 v1, v117, v2
	v_max_f32_e32 v2, 0, v10
	v_fmac_f32_e32 v1, v118, v2
	v_max_f32_e32 v2, 0, v11
	v_fmac_f32_e32 v1, v119, v2
	v_max_f32_e32 v2, 0, v12
	v_fmac_f32_e32 v1, v120, v2
	v_max_f32_e32 v2, 0, v13
	v_fmac_f32_e32 v1, v121, v2
	v_max_f32_e32 v2, 0, v14
	v_fmamk_f32 v0, v0, 0x45800000, v226
	v_cvt_i32_f32_e32 v0, v0
	v_fmac_f32_e32 v1, v122, v2
	v_max_f32_e32 v2, 0, v15
	v_fmac_f32_e32 v1, v123, v2
	v_fmamk_f32 v1, v1, 0x45800000, v226
	v_med3_i32 v0, v0, 1, s33
	v_cmp_le_i32_e32 vcc, v17, v236
	v_cvt_i32_f32_e32 v1, v1
	s_nop 0
	v_cndmask_b32_e32 v0, 0, v0, vcc
	ds_write_b16 v238, v0 offset:512
	v_bfe_u32 v0, v0, 8, 8
	v_lshl_add_u32 v0, v0, 2, v216
	ds_add_u32 v0, v227
	v_med3_i32 v0, v1, 1, s33
	v_cmp_le_i32_e32 vcc, v17, v237
	s_nop 1
	v_cndmask_b32_e32 v0, 0, v0, vcc
	ds_write_b16 v238, v0 offset:16896
	v_bfe_u32 v0, v0, 8, 8
	v_lshl_add_u32 v0, v0, 2, v218
	ds_add_u32 v0, v227
.LBB0_367:
	s_andn2_b64 vcc, exec, s[20:21]
	s_add_i32 s20, s25, 32
	s_cbranch_vccnz .LBB0_364
	s_waitcnt vmcnt(7)
	v_mfma_f32_32x32x16_f16 v[42:57], v[60:63], v[184:187], 0
	s_cmp_lt_u32 s20, s22
	s_cselect_b32 s21, s20, s27
	s_add_i32 s27, s25, 40
	s_cmp_lt_u32 s27, s22
	s_nop 1
	v_lshl_add_u32 v0, s21, 5, v233
	s_cselect_b32 s21, s27, s21
	v_ashrrev_i32_e32 v1, 31, v0
	s_waitcnt vmcnt(6)
	v_mfma_f32_32x32x16_f16 v[42:57], v[64:67], v[172:175], v[42:57]
	v_lshl_add_u32 v2, s21, 5, v233
	v_lshlrev_b64 v[0:1], 7, v[0:1]
	v_ashrrev_i32_e32 v3, 31, v2
	v_lshl_add_u64 v[0:1], v[202:203], 0, v[0:1]
	v_lshlrev_b64 v[2:3], 7, v[2:3]
	v_lshl_add_u64 v[2:3], v[202:203], 0, v[2:3]
	global_load_dwordx4 v[140:143], v[0:1], off
	global_load_dwordx4 v[144:147], v[0:1], off offset:1024
	global_load_dwordx4 v[124:127], v[2:3], off
	global_load_dwordx4 v[128:131], v[2:3], off offset:1024
	global_load_dwordx4 v[148:151], v[0:1], off offset:2048
	global_load_dwordx4 v[152:155], v[0:1], off offset:3072
	global_load_dwordx4 v[132:135], v[2:3], off offset:2048
	global_load_dwordx4 v[136:139], v[2:3], off offset:3072
	s_waitcnt vmcnt(11)
	v_mfma_f32_32x32x16_f16 v[42:57], v[68:71], v[164:167], v[42:57]
	v_add_u32_e32 v58, 0xffff0400, v238
	s_cmp_ge_i32 s25, s24
	s_waitcnt vmcnt(10)
; #define LAS __attribute__((address_space(3)))
; template <int MODE> __device__ __forceinline__ void indexer_pair(LAS unsigned char* lds, const GAS f16* KI, int b, int t0, int ntiles, int tile, int n, int g,
;         const h8 (&A)[2][4], const float (&w)[2][2][8], const h8 (&BA)[4], const h8 (&BB)[4], h8 (&NA)[4], h8 (&NB)[4]) {
;     ...
;         for (int mt = 0; mt < 2; ++mt) { cA[mt] = __builtin_amdgcn_mfma_f32_32x32x16_f16(A[mt][0], BA[0], f32x16{}, 0, 0, 0); cB[mt] = __builtin_amdgcn_mfma_f32_32x32x16_f16(A[mt][0], BB[0], f32x16{}, 0, 0, 0); }
; #pragma unroll
;         for (int kk = 1; kk < 4; ++kk)
; #pragma unroll
;             for (int mt = 0; mt < 2; ++mt) { cA[mt] = __builtin_amdgcn_mfma_f32_32x32x16_f16(A[mt][kk], BA[kk], cA[mt], 0, 0, 0); cB[mt] = __builtin_amdgcn_mfma_f32_32x32x16_f16(A[mt][kk], BB[kk], cB[mt], 0, 0, 0); }
; #pragma unroll
;         for (int u = 0; u < 2; ++u) {
;             const int s = (tile + u * NW) * 32 + n;
;             if (u == 0 || hasB) {
; #pragma unroll
;                 for (int mt = 0; mt < 2; ++mt)
; #pragma unroll
;                     for (int qq = 0; qq < 2; ++qq) {
;                         float sc = 0.f;
; #pragma unroll
;                         for (int h = 0; h < 8; ++h) sc += w[mt][qq][h] * fmaxf(u ? cB[mt][8 * qq + h] : cA[mt][8 * qq + h], 0.f);
;                         const int ql = 4 * mt + 2 * g + qq;
;                         int key = (int)(sc * 4096.f + 32768.5f);
;                         key = key < 1 ? 1 : (key > 65535 ? 65535 : key);
;                         if (s > t0 + ql) key = 0;
;                         KS[ql * SEQ + s] = (unsigned short)key;
;                         __hip_atomic_fetch_add((LAS unsigned*)(lds + 131072) + ql * 256 + (key >> 8), 1u, __ATOMIC_RELAXED, __HIP_MEMORY_SCOPE_WORKGROUP);
;                     }
;             }
;         }
	v_mfma_f32_32x32x16_f16 v[42:57], v[72:75], v[160:163], v[42:57]
	v_mfma_f32_32x32x16_f16 v[16:31], v[60:63], v[176:179], 0
	s_nop 10
	v_max_f32_e32 v0, 0, v42
	v_max_f32_e32 v1, 0, v43
	v_max_f32_e32 v2, 0, v44
	v_fma_f32 v0, v76, v0, 0
	v_max_f32_e32 v3, 0, v45
	v_fmac_f32_e32 v0, v77, v1
	v_max_f32_e32 v4, v46, v46
	v_fmac_f32_e32 v0, v78, v2
	v_fmac_f32_e32 v0, v79, v3
	v_max_f32_e32 v1, 0, v4
	v_fmac_f32_e32 v0, v80, v1
	v_max_f32_e32 v1, 0, v47
	v_mfma_f32_32x32x16_f16 v[32:47], v[92:95], v[184:187], 0
	v_fmac_f32_e32 v0, v81, v1
	v_max_f32_e32 v1, 0, v48
	v_fmac_f32_e32 v0, v82, v1
	v_max_f32_e32 v1, 0, v49
	v_mfma_f32_32x32x16_f16 v[32:47], v[96:99], v[172:175], v[32:47]
	v_fmac_f32_e32 v0, v83, v1
	v_fmamk_f32 v0, v0, 0x45800000, v226
	v_cvt_i32_f32_e32 v48, v0
	v_add_u32_e32 v49, 0x200, v239
	v_cmp_le_i32_e32 vcc, v49, v234
	v_med3_i32 v48, v48, 1, s33
	v_mfma_f32_32x32x16_f16 v[32:47], v[100:103], v[164:167], v[32:47]
	v_cndmask_b32_e32 v48, 0, v48, vcc
	ds_write_b16 v58, v48
	v_bfe_u32 v48, v48, 8, 8
	v_lshl_add_u32 v48, v48, 2, v212
	ds_add_u32 v48, v227
	v_max_f32_e32 v48, 0, v50
	v_mfma_f32_32x32x16_f16 v[32:47], v[104:107], v[160:163], v[32:47]
	v_max_f32_e32 v50, 0, v51
	v_fma_f32 v48, v84, v48, 0
	v_fmac_f32_e32 v48, v85, v50
	v_max_f32_e32 v50, 0, v52
	v_fmac_f32_e32 v48, v86, v50
	v_max_f32_e32 v50, 0, v53
	v_fmac_f32_e32 v48, v87, v50
	v_max_f32_e32 v50, 0, v54
	s_nop 3
	v_max_f32_e32 v32, 0, v32
	v_fmac_f32_e32 v48, v88, v50
	v_max_f32_e32 v50, 0, v55
	v_max_f32_e32 v33, 0, v33
	v_fma_f32 v32, v108, v32, 0
	v_fmac_f32_e32 v48, v89, v50
	v_max_f32_e32 v50, 0, v56
	v_fmac_f32_e32 v32, v109, v33
	v_max_f32_e32 v33, 0, v34
	v_fmac_f32_e32 v48, v90, v50
	v_max_f32_e32 v50, 0, v57
	v_fmac_f32_e32 v32, v110, v33
	v_max_f32_e32 v33, 0, v35
	v_fmac_f32_e32 v48, v91, v50
	v_fmac_f32_e32 v32, v111, v33
	v_max_f32_e32 v33, 0, v36
	v_fmamk_f32 v48, v48, 0x45800000, v226
	v_cvt_i32_f32_e32 v48, v48
	v_fmac_f32_e32 v32, v112, v33
	v_max_f32_e32 v33, 0, v37
	v_fmac_f32_e32 v32, v113, v33
	v_max_f32_e32 v33, 0, v38
	v_med3_i32 v48, v48, 1, s33
	v_cmp_le_i32_e32 vcc, v49, v235
	v_fmac_f32_e32 v32, v114, v33
	v_max_f32_e32 v33, 0, v39
	v_mfma_f32_32x32x16_f16 v[0:15], v[92:95], v[176:179], 0
	v_cndmask_b32_e32 v48, 0, v48, vcc
	v_add_u32_e32 v50, 0xffff4400, v238
	v_fmac_f32_e32 v32, v115, v33
	v_bfe_u32 v33, v48, 8, 8
	ds_write_b16 v50, v48
	v_lshl_add_u32 v33, v33, 2, v214
	ds_add_u32 v33, v227
	v_max_f32_e32 v33, 0, v40
	v_max_f32_e32 v34, 0, v41
	v_fma_f32 v33, v116, v33, 0
	v_fmac_f32_e32 v33, v117, v34
	v_max_f32_e32 v34, 0, v42
	v_mfma_f32_32x32x16_f16 v[16:31], v[64:67], v[168:171], v[16:31]
	v_fmac_f32_e32 v33, v118, v34
	v_max_f32_e32 v34, 0, v43
	v_fmac_f32_e32 v33, v119, v34
	v_max_f32_e32 v34, 0, v44
	v_fmac_f32_e32 v33, v120, v34
	v_mfma_f32_32x32x16_f16 v[0:15], v[96:99], v[168:171], v[0:15]
	v_max_f32_e32 v34, 0, v45
	v_fmac_f32_e32 v33, v121, v34
	v_max_f32_e32 v34, 0, v46
	v_fmamk_f32 v32, v32, 0x45800000, v226
	v_cvt_i32_f32_e32 v32, v32
	s_waitcnt vmcnt(9)
	v_mfma_f32_32x32x16_f16 v[16:31], v[68:71], v[180:183], v[16:31]
	v_fmac_f32_e32 v33, v122, v34
	v_max_f32_e32 v34, 0, v47
	v_fmac_f32_e32 v33, v123, v34
	v_fmamk_f32 v33, v33, 0x45800000, v226
	v_med3_i32 v32, v32, 1, s33
	v_cmp_le_i32_e32 vcc, v49, v236
	v_mfma_f32_32x32x16_f16 v[0:15], v[100:103], v[180:183], v[0:15]
	v_cvt_i32_f32_e32 v33, v33
	v_cndmask_b32_e32 v32, 0, v32, vcc
	ds_write_b16 v238, v32 offset:1024
	v_bfe_u32 v32, v32, 8, 8
	v_lshl_add_u32 v32, v32, 2, v216
	ds_add_u32 v32, v227
	v_med3_i32 v32, v33, 1, s33
	s_waitcnt vmcnt(8)
	v_mfma_f32_32x32x16_f16 v[16:31], v[72:75], v[156:159], v[16:31]
	v_cmp_le_i32_e32 vcc, v49, v237
	s_nop 1
	v_cndmask_b32_e32 v32, 0, v32, vcc
	ds_write_b16 v238, v32 offset:17408
	v_bfe_u32 v32, v32, 8, 8
	v_lshl_add_u32 v32, v32, 2, v218
	v_mfma_f32_32x32x16_f16 v[0:15], v[104:107], v[156:159], v[0:15]
	ds_add_u32 v32, v227
	s_cbranch_scc1 .LBB0_364
	s_nop 1
	v_max_f32_e32 v16, 0, v16
	v_max_f32_e32 v17, 0, v17
	v_fma_f32 v16, v76, v16, 0
	v_fmac_f32_e32 v16, v77, v17
	v_max_f32_e32 v17, 0, v18
	v_fmac_f32_e32 v16, v78, v17
	v_max_f32_e32 v17, 0, v19
	v_fmac_f32_e32 v16, v79, v17
	v_max_f32_e32 v17, 0, v20
	v_fmac_f32_e32 v16, v80, v17
	v_max_f32_e32 v17, 0, v21
	v_fmac_f32_e32 v16, v81, v17
	v_max_f32_e32 v17, 0, v22
	v_fmac_f32_e32 v16, v82, v17
	v_max_f32_e32 v17, 0, v23
	v_fmac_f32_e32 v16, v83, v17
	v_fmamk_f32 v16, v16, 0x45800000, v226
	v_cvt_i32_f32_e32 v16, v16
	v_add_u32_e32 v17, 0x300, v239
	v_cmp_le_i32_e32 vcc, v17, v234
	v_add_u32_e32 v18, 0xffff0600, v238
	v_med3_i32 v16, v16, 1, s33
	v_cndmask_b32_e32 v16, 0, v16, vcc
	ds_write_b16 v18, v16
	v_max_f32_e32 v18, 0, v24
	v_max_f32_e32 v19, 0, v25
	v_fma_f32 v18, v84, v18, 0
	v_fmac_f32_e32 v18, v85, v19
	v_max_f32_e32 v19, 0, v26
	v_fmac_f32_e32 v18, v86, v19
	v_max_f32_e32 v19, 0, v27
	v_fmac_f32_e32 v18, v87, v19
	v_max_f32_e32 v19, 0, v28
	v_max_f32_e32 v0, 0, v0
	v_fmac_f32_e32 v18, v88, v19
	v_max_f32_e32 v19, 0, v29
	v_max_f32_e32 v1, 0, v1
	v_fma_f32 v0, v108, v0, 0
	v_fmac_f32_e32 v18, v89, v19
	v_max_f32_e32 v19, 0, v30
	v_fmac_f32_e32 v0, v109, v1
	v_max_f32_e32 v1, 0, v2
	v_fmac_f32_e32 v18, v90, v19
	v_max_f32_e32 v19, 0, v31
	v_fmac_f32_e32 v0, v110, v1
	v_max_f32_e32 v1, 0, v3
	v_fmac_f32_e32 v18, v91, v19
	v_fmac_f32_e32 v0, v111, v1
	v_max_f32_e32 v1, 0, v4
	v_fmamk_f32 v18, v18, 0x45800000, v226
	v_cvt_i32_f32_e32 v18, v18
	v_fmac_f32_e32 v0, v112, v1
	v_max_f32_e32 v1, 0, v5
	v_bfe_u32 v16, v16, 8, 8
	v_fmac_f32_e32 v0, v113, v1
	v_max_f32_e32 v1, 0, v6
	v_lshl_add_u32 v16, v16, 2, v212
	ds_add_u32 v16, v227
	v_med3_i32 v16, v18, 1, s33
	v_cmp_le_i32_e32 vcc, v17, v235
	v_fmac_f32_e32 v0, v114, v1
	v_max_f32_e32 v1, 0, v7
	v_cndmask_b32_e32 v16, 0, v16, vcc
	v_add_u32_e32 v18, 0xffff4600, v238
	v_fmac_f32_e32 v0, v115, v1
	v_bfe_u32 v1, v16, 8, 8
	ds_write_b16 v18, v16
	v_lshl_add_u32 v1, v1, 2, v214
	ds_add_u32 v1, v227
	v_max_f32_e32 v1, 0, v8
	v_max_f32_e32 v2, 0, v9
	v_fma_f32 v1, v116, v1, 0
	v_fmac_f32_e32 v1, v117, v2
	v_max_f32_e32 v2, 0, v10
	v_fmac_f32_e32 v1, v118, v2
	v_max_f32_e32 v2, 0, v11
	v_fmac_f32_e32 v1, v119, v2
	v_max_f32_e32 v2, 0, v12
	v_fmac_f32_e32 v1, v120, v2
	v_max_f32_e32 v2, 0, v13
	v_fmac_f32_e32 v1, v121, v2
	v_max_f32_e32 v2, 0, v14
	v_fmamk_f32 v0, v0, 0x45800000, v226
	v_cvt_i32_f32_e32 v0, v0
	v_fmac_f32_e32 v1, v122, v2
	v_max_f32_e32 v2, 0, v15
	v_fmac_f32_e32 v1, v123, v2
	v_fmamk_f32 v1, v1, 0x45800000, v226
	v_med3_i32 v0, v0, 1, s33
	v_cmp_le_i32_e32 vcc, v17, v236
	v_cvt_i32_f32_e32 v1, v1
	s_nop 0
	v_cndmask_b32_e32 v0, 0, v0, vcc
	ds_write_b16 v238, v0 offset:1536
	v_bfe_u32 v0, v0, 8, 8
	v_lshl_add_u32 v0, v0, 2, v216
	ds_add_u32 v0, v227
	v_med3_i32 v0, v1, 1, s33
	v_cmp_le_i32_e32 vcc, v17, v237
	s_nop 1
	v_cndmask_b32_e32 v0, 0, v0, vcc
	ds_write_b16 v238, v0 offset:17920
	v_bfe_u32 v0, v0, 8, 8
	v_lshl_add_u32 v0, v0, 2, v218
	ds_add_u32 v0, v227
	s_branch .LBB0_364

; #define LAS __attribute__((address_space(3)))
; template <int MODE> __device__ __forceinline__ void indexer_pair(LAS unsigned char* lds, const GAS f16* KI, int b, int t0, int ntiles, int tile, int n, int g,
;         const h8 (&A)[2][4], const float (&w)[2][2][8], const h8 (&BA)[4], const h8 (&BB)[4], h8 (&NA)[4], h8 (&NB)[4]) {
;     ...
;         for (int mt = 0; mt < 2; ++mt) { cA[mt] = __builtin_amdgcn_mfma_f32_32x32x16_f16(A[mt][0], BA[0], f32x16{}, 0, 0, 0); cB[mt] = __builtin_amdgcn_mfma_f32_32x32x16_f16(A[mt][0], BB[0], f32x16{}, 0, 0, 0); }
; #pragma unroll
;         for (int kk = 1; kk < 4; ++kk)
; #pragma unroll
;             for (int mt = 0; mt < 2; ++mt) { cA[mt] = __builtin_amdgcn_mfma_f32_32x32x16_f16(A[mt][kk], BA[kk], cA[mt], 0, 0, 0); cB[mt] = __builtin_amdgcn_mfma_f32_32x32x16_f16(A[mt][kk], BB[kk], cB[mt], 0, 0, 0); }
; #pragma unroll
;         for (int u = 0; u < 2; ++u) {
;             const int s = (tile + u * NW) * 32 + n;
;             if (u == 0 || hasB) {
; #pragma unroll
;                 for (int mt = 0; mt < 2; ++mt)
; #pragma unroll
;                     for (int qq = 0; qq < 2; ++qq) {
;                         float sc = 0.f;
; #pragma unroll
;                         for (int h = 0; h < 8; ++h) sc += w[mt][qq][h] * fmaxf(u ? cB[mt][8 * qq + h] : cA[mt][8 * qq + h], 0.f);
;                         const int ql = 4 * mt + 2 * g + qq;
;                         int key = (int)(sc * 4096.f + 32768.5f);
;                         key = key < 1 ? 1 : (key > 65535 ? 65535 : key);
;                         if (s > t0 + ql) key = 0;
;                         KS[ql * SEQ + s] = (unsigned short)key;
;                         __hip_atomic_fetch_add((LAS unsigned*)(lds + 131072) + ql * 256 + (key >> 8), 1u, __ATOMIC_RELAXED, __HIP_MEMORY_SCOPE_WORKGROUP);
.LBB0_451:
	s_waitcnt vmcnt(3)
	v_mfma_f32_32x32x16_f16 v[28:43], v[60:63], v[140:143], 0
	s_add_i32 s27, s25, 16
	s_cmp_lt_u32 s27, s22
	s_cselect_b64 s[20:21], -1, 0
	s_and_b64 s[50:51], s[20:21], exec
	s_cselect_b32 s36, s27, s25
	s_add_i32 s37, s25, 24
	s_cmp_lt_u32 s37, s22
	s_waitcnt vmcnt(2)
	v_mfma_f32_32x32x16_f16 v[28:43], v[64:67], v[144:147], v[28:43]
	s_cselect_b32 s37, s37, s36
	v_lshl_add_u32 v0, s36, 5, v233
	v_ashrrev_i32_e32 v1, 31, v0
	v_lshl_add_u32 v2, s37, 5, v233
	v_lshlrev_b64 v[0:1], 7, v[0:1]
	v_ashrrev_i32_e32 v3, 31, v2
	v_lshl_add_u64 v[0:1], v[202:203], 0, v[0:1]
	s_waitcnt vmcnt(1)
	v_mfma_f32_32x32x16_f16 v[28:43], v[68:71], v[148:151], v[28:43]
	v_lshlrev_b64 v[2:3], 7, v[2:3]
	s_waitcnt vmcnt(0)
	v_lshl_add_u64 v[156:157], v[202:203], 0, v[2:3]
	global_load_dwordx4 v[184:187], v[0:1], off
	global_load_dwordx4 v[172:175], v[0:1], off offset:1024
	global_load_dwordx4 v[176:179], v[156:157], off
	global_load_dwordx4 v[168:171], v[156:157], off offset:1024
	global_load_dwordx4 v[164:167], v[0:1], off offset:2048
	global_load_dwordx4 v[160:163], v[0:1], off offset:3072
	global_load_dwordx4 v[180:183], v[156:157], off offset:2048
	s_nop 0
	global_load_dwordx4 v[156:159], v[156:157], off offset:3072
	v_cmp_le_i32_e32 vcc, v239, v234
	s_cmp_ge_i32 s25, s23
	s_waitcnt vmcnt(8)
	v_mfma_f32_32x32x16_f16 v[28:43], v[72:75], v[152:155], v[28:43]
	v_mfma_f32_32x32x16_f16 v[44:59], v[92:95], v[140:143], 0
	s_nop 10
	v_max_f32_e32 v0, 0, v28
	v_max_f32_e32 v1, 0, v29
	v_max_f32_e32 v2, 0, v30
	v_fma_f32 v0, v76, v0, 0
	v_max_f32_e32 v3, 0, v31
	v_fmac_f32_e32 v0, v77, v1
	v_fmac_f32_e32 v0, v78, v2
	v_max_f32_e32 v1, 0, v32
	v_fmac_f32_e32 v0, v79, v3
	v_fmac_f32_e32 v0, v80, v1
	v_max_f32_e32 v1, 0, v33
	v_fmac_f32_e32 v0, v81, v1
	v_max_f32_e32 v1, 0, v34
	v_fmac_f32_e32 v0, v82, v1
	v_max_f32_e32 v1, 0, v35
	v_fmac_f32_e32 v0, v83, v1
	v_fmamk_f32 v0, v0, 0x45800000, v226
	v_cvt_i32_f32_e32 v32, v0
	v_add_u32_e32 v33, 0xffff0000, v238
	v_mfma_f32_32x32x16_f16 v[44:59], v[96:99], v[144:147], v[44:59]
	v_max_f32_e32 v34, 0, v37
	v_med3_i32 v32, v32, 1, s62
	v_cndmask_b32_e32 v32, 0, v32, vcc
	ds_write_b16 v33, v32
	v_max_f32_e32 v33, 0, v36
	v_fma_f32 v33, v84, v33, 0
	v_fmac_f32_e32 v33, v85, v34
	v_max_f32_e32 v34, 0, v38
	v_fmac_f32_e32 v33, v86, v34
	v_max_f32_e32 v34, 0, v39
	v_fmac_f32_e32 v33, v87, v34
	v_max_f32_e32 v34, 0, v40
	v_mfma_f32_32x32x16_f16 v[44:59], v[100:103], v[148:151], v[44:59]
	v_fmac_f32_e32 v33, v88, v34
	v_max_f32_e32 v34, 0, v41
	v_fmac_f32_e32 v33, v89, v34
	v_max_f32_e32 v34, 0, v42
	v_fmac_f32_e32 v33, v90, v34
	v_max_f32_e32 v34, 0, v43
	v_fmac_f32_e32 v33, v91, v34
	v_mfma_f32_32x32x16_f16 v[44:59], v[104:107], v[152:155], v[44:59]
	v_fmamk_f32 v33, v33, 0x45800000, v226
	v_cvt_i32_f32_e32 v33, v33
	v_bfe_u32 v32, v32, 8, 8
	v_lshl_add_u32 v32, v32, 2, v212
	ds_add_u32 v32, v227
	v_med3_i32 v32, v33, 1, s62
	v_cmp_le_i32_e32 vcc, v239, v235
	v_add_u32_e32 v33, 0xffff4000, v238
	s_nop 3
	v_max_f32_e32 v34, 0, v45
	v_cndmask_b32_e32 v32, 0, v32, vcc
	ds_write_b16 v33, v32
	v_max_f32_e32 v33, 0, v44
	v_fma_f32 v33, v108, v33, 0
	v_fmac_f32_e32 v33, v109, v34
	v_max_f32_e32 v34, 0, v46
	v_fmac_f32_e32 v33, v110, v34
	v_max_f32_e32 v34, 0, v47
	v_fmac_f32_e32 v33, v111, v34
	v_max_f32_e32 v34, 0, v48
	v_fmac_f32_e32 v33, v112, v34
	v_max_f32_e32 v34, 0, v49
	v_fmac_f32_e32 v33, v113, v34
	v_max_f32_e32 v34, 0, v50
	v_fmac_f32_e32 v33, v114, v34
	v_max_f32_e32 v34, 0, v51
	v_fmac_f32_e32 v33, v115, v34
	v_fmamk_f32 v33, v33, 0x45800000, v226
	v_cvt_i32_f32_e32 v33, v33
	v_mfma_f32_32x32x16_f16 v[16:31], v[60:63], v[124:127], 0
	v_bfe_u32 v32, v32, 8, 8
	v_lshl_add_u32 v32, v32, 2, v214
	ds_add_u32 v32, v227
	v_med3_i32 v32, v33, 1, s62
	v_max_f32_e32 v33, 0, v52
	v_max_f32_e32 v34, 0, v53
	v_mfma_f32_32x32x16_f16 v[0:15], v[92:95], v[124:127], 0
	v_fma_f32 v33, v116, v33, 0
	v_fmac_f32_e32 v33, v117, v34
	v_max_f32_e32 v34, 0, v54
	v_fmac_f32_e32 v33, v118, v34
	v_max_f32_e32 v34, 0, v55
	v_mfma_f32_32x32x16_f16 v[16:31], v[64:67], v[128:131], v[16:31]
	v_fmac_f32_e32 v33, v119, v34
	v_max_f32_e32 v34, 0, v56
	v_fmac_f32_e32 v33, v120, v34
	v_max_f32_e32 v34, 0, v57
	v_mfma_f32_32x32x16_f16 v[0:15], v[96:99], v[128:131], v[0:15]
	v_fmac_f32_e32 v33, v121, v34
	v_max_f32_e32 v34, 0, v58
	v_fmac_f32_e32 v33, v122, v34
	v_max_f32_e32 v34, 0, v59
	v_fmac_f32_e32 v33, v123, v34
	v_mfma_f32_32x32x16_f16 v[16:31], v[68:71], v[132:135], v[16:31]
	v_fmamk_f32 v33, v33, 0x45800000, v226
	v_cmp_le_i32_e32 vcc, v239, v236
	v_cvt_i32_f32_e32 v33, v33
	s_nop 0
	v_cndmask_b32_e32 v32, 0, v32, vcc
	ds_write_b16 v238, v32
	v_bfe_u32 v32, v32, 8, 8
	v_mfma_f32_32x32x16_f16 v[0:15], v[100:103], v[132:135], v[0:15]
	v_lshl_add_u32 v32, v32, 2, v216
	ds_add_u32 v32, v227
	v_med3_i32 v32, v33, 1, s62
	v_cmp_le_i32_e32 vcc, v239, v237
	s_nop 1
	v_cndmask_b32_e32 v32, 0, v32, vcc
	v_mfma_f32_32x32x16_f16 v[16:31], v[72:75], v[136:139], v[16:31]
	ds_write_b16 v238, v32 offset:16384
	v_bfe_u32 v32, v32, 8, 8
	v_lshl_add_u32 v32, v32, 2, v218
	ds_add_u32 v32, v227
	v_mfma_f32_32x32x16_f16 v[0:15], v[104:107], v[136:139], v[0:15]
	s_cbranch_scc1 .LBB0_453
; #define LAS __attribute__((address_space(3)))
; #define GAS __attribute__((address_space(1)))
; template <int MODE> __device__ __forceinline__ void indexer_pair(LAS unsigned char* lds, const GAS f16* KI, int b, int t0, int ntiles, int tile, int n, int g,
;         const h8 (&A)[2][4], const float (&w)[2][2][8], const h8 (&BA)[4], const h8 (&BB)[4], h8 (&NA)[4], h8 (&NB)[4]) {
;     ...
;         const int tna = (tile + 2 * NW < ntiles) ? tile + 2 * NW : tile, tnb = (tile + 3 * NW < ntiles) ? tile + 3 * NW : tna;
;         const GAS h8* pa = (const GAS h8*)(KI + (size_t)(b * SEQ + tna * 32 + n) * 64 + 32 * g);
;         const GAS h8* pb = (const GAS h8*)(KI + (size_t)(b * SEQ + tnb * 32 + n) * 64 + 32 * g);
;         #pragma unroll
;         for (int kk = 0; kk < 4; ++kk) { NA[kk] = pa[kk]; NB[kk] = pb[kk]; }
;         f32x16 cA[2], cB[2];
; #pragma unroll
;         for (int mt = 0; mt < 2; ++mt) { cA[mt] = __builtin_amdgcn_mfma_f32_32x32x16_f16(A[mt][0], BA[0], f32x16{}, 0, 0, 0); cB[mt] = __builtin_amdgcn_mfma_f32_32x32x16_f16(A[mt][0], BB[0], f32x16{}, 0, 0, 0); }
; #pragma unroll
;         for (int kk = 1; kk < 4; ++kk)
; #pragma unroll
;             for (int mt = 0; mt < 2; ++mt) { cA[mt] = __builtin_amdgcn_mfma_f32_32x32x16_f16(A[mt][kk], BA[kk], cA[mt], 0, 0, 0); cB[mt] = __builtin_amdgcn_mfma_f32_32x32x16_f16(A[mt][kk], BB[kk], cB[mt], 0, 0, 0); }
; #pragma unroll
;         for (int u = 0; u < 2; ++u) {
;             const int s = (tile + u * NW) * 32 + n;
;             if (u == 0 || hasB) {
; #pragma unroll
;                 for (int mt = 0; mt < 2; ++mt)
; #pragma unroll
;                     for (int qq = 0; qq < 2; ++qq) {
;                         float sc = 0.f;
; #pragma unroll
;                         for (int h = 0; h < 8; ++h) sc += w[mt][qq][h] * fmaxf(u ? cB[mt][8 * qq + h] : cA[mt][8 * qq + h], 0.f);
;                         const int ql = 4 * mt + 2 * g + qq;
;                         int key = (int)(sc * 4096.f + 32768.5f);
;                         key = key < 1 ? 1 : (key > 65535 ? 65535 : key);
;                         if (s > t0 + ql) key = 0;
;                         KS[ql * SEQ + s] = (unsigned short)key;
;                         __hip_atomic_fetch_add((LAS unsigned*)(lds + 131072) + ql * 256 + (key >> 8), 1u, __ATOMIC_RELAXED, __HIP_MEMORY_SCOPE_WORKGROUP);
;                     }
	s_nop 5
	v_max_f32_e32 v16, 0, v16
	v_max_f32_e32 v17, 0, v17
	v_fma_f32 v16, v76, v16, 0
	v_fmac_f32_e32 v16, v77, v17
	v_max_f32_e32 v17, 0, v18
	v_fmac_f32_e32 v16, v78, v17
	v_max_f32_e32 v17, 0, v19
	v_fmac_f32_e32 v16, v79, v17
	v_max_f32_e32 v17, 0, v20
	v_fmac_f32_e32 v16, v80, v17
	v_max_f32_e32 v17, 0, v21
	v_fmac_f32_e32 v16, v81, v17
	v_max_f32_e32 v17, 0, v22
	v_fmac_f32_e32 v16, v82, v17
	v_max_f32_e32 v17, 0, v23
	v_fmac_f32_e32 v16, v83, v17
	v_fmamk_f32 v16, v16, 0x45800000, v226
	v_cvt_i32_f32_e32 v16, v16
	v_add_u32_e32 v17, 0x100, v239
	v_cmp_le_i32_e32 vcc, v17, v234
	v_add_u32_e32 v18, 0xffff0200, v238
	v_med3_i32 v16, v16, 1, s62
	v_cndmask_b32_e32 v16, 0, v16, vcc
	ds_write_b16 v18, v16
	v_max_f32_e32 v18, 0, v24
	v_max_f32_e32 v19, 0, v25
	v_fma_f32 v18, v84, v18, 0
	v_fmac_f32_e32 v18, v85, v19
	v_max_f32_e32 v19, 0, v26
	v_fmac_f32_e32 v18, v86, v19
	v_max_f32_e32 v19, 0, v27
	v_fmac_f32_e32 v18, v87, v19
	v_max_f32_e32 v19, 0, v28
	v_max_f32_e32 v0, 0, v0
	v_fmac_f32_e32 v18, v88, v19
	v_max_f32_e32 v19, 0, v29
	v_max_f32_e32 v1, 0, v1
	v_fma_f32 v0, v108, v0, 0
	v_fmac_f32_e32 v18, v89, v19
	v_max_f32_e32 v19, 0, v30
	v_fmac_f32_e32 v0, v109, v1
	v_max_f32_e32 v1, 0, v2
	v_fmac_f32_e32 v18, v90, v19
	v_max_f32_e32 v19, 0, v31
	v_fmac_f32_e32 v0, v110, v1
	v_max_f32_e32 v1, 0, v3
	v_fmac_f32_e32 v18, v91, v19
	v_fmac_f32_e32 v0, v111, v1
	v_max_f32_e32 v1, 0, v4
	v_fmamk_f32 v18, v18, 0x45800000, v226
	v_cvt_i32_f32_e32 v18, v18
	v_fmac_f32_e32 v0, v112, v1
	v_max_f32_e32 v1, 0, v5
	v_bfe_u32 v16, v16, 8, 8
	v_fmac_f32_e32 v0, v113, v1
	v_max_f32_e32 v1, 0, v6
	v_lshl_add_u32 v16, v16, 2, v212
	ds_add_u32 v16, v227
	v_med3_i32 v16, v18, 1, s62
	v_cmp_le_i32_e32 vcc, v17, v235
	v_fmac_f32_e32 v0, v114, v1
	v_max_f32_e32 v1, 0, v7
	v_cndmask_b32_e32 v16, 0, v16, vcc
	v_add_u32_e32 v18, 0xffff4200, v238
	v_fmac_f32_e32 v0, v115, v1
	v_bfe_u32 v1, v16, 8, 8
	ds_write_b16 v18, v16
	v_lshl_add_u32 v1, v1, 2, v214
	ds_add_u32 v1, v227
	v_max_f32_e32 v1, 0, v8
	v_max_f32_e32 v2, 0, v9
	v_fma_f32 v1, v116, v1, 0
	v_fmac_f32_e32 v1, v117, v2
	v_max_f32_e32 v2, 0, v10
	v_fmac_f32_e32 v1, v118, v2
	v_max_f32_e32 v2, 0, v11
	v_fmac_f32_e32 v1, v119, v2
	v_max_f32_e32 v2, 0, v12
	v_fmac_f32_e32 v1, v120, v2
	v_max_f32_e32 v2, 0, v13
	v_fmac_f32_e32 v1, v121, v2
	v_max_f32_e32 v2, 0, v14
	v_fmamk_f32 v0, v0, 0x45800000, v226
	v_cvt_i32_f32_e32 v0, v0
	v_fmac_f32_e32 v1, v122, v2
	v_max_f32_e32 v2, 0, v15
	v_fmac_f32_e32 v1, v123, v2
	v_fmamk_f32 v1, v1, 0x45800000, v226
	v_med3_i32 v0, v0, 1, s62
	v_cmp_le_i32_e32 vcc, v17, v236
	v_cvt_i32_f32_e32 v1, v1
	s_nop 0
	v_cndmask_b32_e32 v0, 0, v0, vcc
	ds_write_b16 v238, v0 offset:512
	v_bfe_u32 v0, v0, 8, 8
	v_lshl_add_u32 v0, v0, 2, v216
	ds_add_u32 v0, v227
	v_med3_i32 v0, v1, 1, s62
	v_cmp_le_i32_e32 vcc, v17, v237
	s_nop 1
	v_cndmask_b32_e32 v0, 0, v0, vcc
	ds_write_b16 v238, v0 offset:16896
	v_bfe_u32 v0, v0, 8, 8
	v_lshl_add_u32 v0, v0, 2, v218
	ds_add_u32 v0, v227
.LBB0_453:
	s_andn2_b64 vcc, exec, s[20:21]
	s_add_i32 s20, s25, 32
	s_cbranch_vccnz .LBB0_450
	s_waitcnt vmcnt(7)
	v_mfma_f32_32x32x16_f16 v[42:57], v[60:63], v[184:187], 0
	s_cmp_lt_u32 s20, s22
	s_cselect_b32 s21, s20, s27
	s_add_i32 s27, s25, 40
	s_cmp_lt_u32 s27, s22
	s_nop 1
	v_lshl_add_u32 v0, s21, 5, v233
	s_cselect_b32 s21, s27, s21
	v_ashrrev_i32_e32 v1, 31, v0
	s_waitcnt vmcnt(6)
	v_mfma_f32_32x32x16_f16 v[42:57], v[64:67], v[172:175], v[42:57]
	v_lshl_add_u32 v2, s21, 5, v233
	v_lshlrev_b64 v[0:1], 7, v[0:1]
	v_ashrrev_i32_e32 v3, 31, v2
	v_lshl_add_u64 v[0:1], v[202:203], 0, v[0:1]
	v_lshlrev_b64 v[2:3], 7, v[2:3]
	v_lshl_add_u64 v[2:3], v[202:203], 0, v[2:3]
	global_load_dwordx4 v[140:143], v[0:1], off
	global_load_dwordx4 v[144:147], v[0:1], off offset:1024
	global_load_dwordx4 v[124:127], v[2:3], off
	global_load_dwordx4 v[128:131], v[2:3], off offset:1024
	global_load_dwordx4 v[148:151], v[0:1], off offset:2048
	global_load_dwordx4 v[152:155], v[0:1], off offset:3072
	global_load_dwordx4 v[132:135], v[2:3], off offset:2048
	global_load_dwordx4 v[136:139], v[2:3], off offset:3072
	s_waitcnt vmcnt(11)
	v_mfma_f32_32x32x16_f16 v[42:57], v[68:71], v[164:167], v[42:57]
	v_add_u32_e32 v58, 0xffff0400, v238
	s_cmp_ge_i32 s25, s24
	s_waitcnt vmcnt(10)
; #define LAS __attribute__((address_space(3)))
; #define GAS __attribute__((address_space(1)))
; template <int MODE> __device__ __forceinline__ void indexer_pair(LAS unsigned char* lds, const GAS f16* KI, int b, int t0, int ntiles, int tile, int n, int g,
;         const h8 (&A)[2][4], const float (&w)[2][2][8], const h8 (&BA)[4], const h8 (&BB)[4], h8 (&NA)[4], h8 (&NB)[4]) {
;     ...
;         const int tna = (tile + 2 * NW < ntiles) ? tile + 2 * NW : tile, tnb = (tile + 3 * NW < ntiles) ? tile + 3 * NW : tna;
;         const GAS h8* pa = (const GAS h8*)(KI + (size_t)(b * SEQ + tna * 32 + n) * 64 + 32 * g);
;         const GAS h8* pb = (const GAS h8*)(KI + (size_t)(b * SEQ + tnb * 32 + n) * 64 + 32 * g);
;         #pragma unroll
;         for (int kk = 0; kk < 4; ++kk) { NA[kk] = pa[kk]; NB[kk] = pb[kk]; }
;         f32x16 cA[2], cB[2];
; #pragma unroll
;         for (int mt = 0; mt < 2; ++mt) { cA[mt] = __builtin_amdgcn_mfma_f32_32x32x16_f16(A[mt][0], BA[0], f32x16{}, 0, 0, 0); cB[mt] = __builtin_amdgcn_mfma_f32_32x32x16_f16(A[mt][0], BB[0], f32x16{}, 0, 0, 0); }
; #pragma unroll
;         for (int kk = 1; kk < 4; ++kk)
; #pragma unroll
;             for (int mt = 0; mt < 2; ++mt) { cA[mt] = __builtin_amdgcn_mfma_f32_32x32x16_f16(A[mt][kk], BA[kk], cA[mt], 0, 0, 0); cB[mt] = __builtin_amdgcn_mfma_f32_32x32x16_f16(A[mt][kk], BB[kk], cB[mt], 0, 0, 0); }
; #pragma unroll
;         for (int u = 0; u < 2; ++u) {
;             const int s = (tile + u * NW) * 32 + n;
;             if (u == 0 || hasB) {
; #pragma unroll
;                 for (int mt = 0; mt < 2; ++mt)
; #pragma unroll
;                     for (int qq = 0; qq < 2; ++qq) {
;                         float sc = 0.f;
; #pragma unroll
;                         for (int h = 0; h < 8; ++h) sc += w[mt][qq][h] * fmaxf(u ? cB[mt][8 * qq + h] : cA[mt][8 * qq + h], 0.f);
;                         const int ql = 4 * mt + 2 * g + qq;
;                         int key = (int)(sc * 4096.f + 32768.5f);
;                         key = key < 1 ? 1 : (key > 65535 ? 65535 : key);
;                         if (s > t0 + ql) key = 0;
;                         KS[ql * SEQ + s] = (unsigned short)key;
;                         __hip_atomic_fetch_add((LAS unsigned*)(lds + 131072) + ql * 256 + (key >> 8), 1u, __ATOMIC_RELAXED, __HIP_MEMORY_SCOPE_WORKGROUP);
;                     }
	v_mfma_f32_32x32x16_f16 v[42:57], v[72:75], v[160:163], v[42:57]
	v_mfma_f32_32x32x16_f16 v[16:31], v[60:63], v[176:179], 0
	s_nop 10
	v_max_f32_e32 v0, 0, v42
	v_max_f32_e32 v1, 0, v43
	v_max_f32_e32 v2, 0, v44
	v_fma_f32 v0, v76, v0, 0
	v_max_f32_e32 v3, 0, v45
	v_fmac_f32_e32 v0, v77, v1
	v_max_f32_e32 v4, v46, v46
	v_fmac_f32_e32 v0, v78, v2
	v_fmac_f32_e32 v0, v79, v3
	v_max_f32_e32 v1, 0, v4
	v_fmac_f32_e32 v0, v80, v1
	v_max_f32_e32 v1, 0, v47
	v_mfma_f32_32x32x16_f16 v[32:47], v[92:95], v[184:187], 0
	v_fmac_f32_e32 v0, v81, v1
	v_max_f32_e32 v1, 0, v48
	v_fmac_f32_e32 v0, v82, v1
	v_max_f32_e32 v1, 0, v49
	v_mfma_f32_32x32x16_f16 v[32:47], v[96:99], v[172:175], v[32:47]
	v_fmac_f32_e32 v0, v83, v1
	v_fmamk_f32 v0, v0, 0x45800000, v226
	v_cvt_i32_f32_e32 v48, v0
	v_add_u32_e32 v49, 0x200, v239
	v_cmp_le_i32_e32 vcc, v49, v234
	v_med3_i32 v48, v48, 1, s62
	v_mfma_f32_32x32x16_f16 v[32:47], v[100:103], v[164:167], v[32:47]
	v_cndmask_b32_e32 v48, 0, v48, vcc
	ds_write_b16 v58, v48
	v_bfe_u32 v48, v48, 8, 8
	v_lshl_add_u32 v48, v48, 2, v212
	ds_add_u32 v48, v227
	v_max_f32_e32 v48, 0, v50
	v_mfma_f32_32x32x16_f16 v[32:47], v[104:107], v[160:163], v[32:47]
	v_max_f32_e32 v50, 0, v51
	v_fma_f32 v48, v84, v48, 0
	v_fmac_f32_e32 v48, v85, v50
	v_max_f32_e32 v50, 0, v52
	v_fmac_f32_e32 v48, v86, v50
	v_max_f32_e32 v50, 0, v53
	v_fmac_f32_e32 v48, v87, v50
	v_max_f32_e32 v50, 0, v54
	s_nop 3
	v_max_f32_e32 v32, 0, v32
	v_fmac_f32_e32 v48, v88, v50
	v_max_f32_e32 v50, 0, v55
	v_max_f32_e32 v33, 0, v33
	v_fma_f32 v32, v108, v32, 0
	v_fmac_f32_e32 v48, v89, v50
	v_max_f32_e32 v50, 0, v56
	v_fmac_f32_e32 v32, v109, v33
	v_max_f32_e32 v33, 0, v34
	v_fmac_f32_e32 v48, v90, v50
	v_max_f32_e32 v50, 0, v57
	v_fmac_f32_e32 v32, v110, v33
	v_max_f32_e32 v33, 0, v35
	v_fmac_f32_e32 v48, v91, v50
	v_fmac_f32_e32 v32, v111, v33
	v_max_f32_e32 v33, 0, v36
	v_fmamk_f32 v48, v48, 0x45800000, v226
	v_cvt_i32_f32_e32 v48, v48
	v_fmac_f32_e32 v32, v112, v33
	v_max_f32_e32 v33, 0, v37
	v_fmac_f32_e32 v32, v113, v33
	v_max_f32_e32 v33, 0, v38
	v_med3_i32 v48, v48, 1, s62
	v_cmp_le_i32_e32 vcc, v49, v235
	v_fmac_f32_e32 v32, v114, v33
	v_max_f32_e32 v33, 0, v39
	v_mfma_f32_32x32x16_f16 v[0:15], v[92:95], v[176:179], 0
	v_cndmask_b32_e32 v48, 0, v48, vcc
	v_add_u32_e32 v50, 0xffff4400, v238
	v_fmac_f32_e32 v32, v115, v33
	v_bfe_u32 v33, v48, 8, 8
	ds_write_b16 v50, v48
	v_lshl_add_u32 v33, v33, 2, v214
	ds_add_u32 v33, v227
	v_max_f32_e32 v33, 0, v40
	v_max_f32_e32 v34, 0, v41
	v_fma_f32 v33, v116, v33, 0
	v_fmac_f32_e32 v33, v117, v34
	v_max_f32_e32 v34, 0, v42
	v_mfma_f32_32x32x16_f16 v[16:31], v[64:67], v[168:171], v[16:31]
	v_fmac_f32_e32 v33, v118, v34
	v_max_f32_e32 v34, 0, v43
	v_fmac_f32_e32 v33, v119, v34
	v_max_f32_e32 v34, 0, v44
	v_fmac_f32_e32 v33, v120, v34
	v_mfma_f32_32x32x16_f16 v[0:15], v[96:99], v[168:171], v[0:15]
	v_max_f32_e32 v34, 0, v45
	v_fmac_f32_e32 v33, v121, v34
	v_max_f32_e32 v34, 0, v46
	v_fmamk_f32 v32, v32, 0x45800000, v226
	v_cvt_i32_f32_e32 v32, v32
	s_waitcnt vmcnt(9)
	v_mfma_f32_32x32x16_f16 v[16:31], v[68:71], v[180:183], v[16:31]
	v_fmac_f32_e32 v33, v122, v34
	v_max_f32_e32 v34, 0, v47
	v_fmac_f32_e32 v33, v123, v34
	v_fmamk_f32 v33, v33, 0x45800000, v226
	v_med3_i32 v32, v32, 1, s62
	v_cmp_le_i32_e32 vcc, v49, v236
	v_mfma_f32_32x32x16_f16 v[0:15], v[100:103], v[180:183], v[0:15]
	v_cvt_i32_f32_e32 v33, v33
	v_cndmask_b32_e32 v32, 0, v32, vcc
	ds_write_b16 v238, v32 offset:1024
	v_bfe_u32 v32, v32, 8, 8
	v_lshl_add_u32 v32, v32, 2, v216
	ds_add_u32 v32, v227
	v_med3_i32 v32, v33, 1, s62
	s_waitcnt vmcnt(8)
	v_mfma_f32_32x32x16_f16 v[16:31], v[72:75], v[156:159], v[16:31]
	v_cmp_le_i32_e32 vcc, v49, v237
	s_nop 1
	v_cndmask_b32_e32 v32, 0, v32, vcc
	ds_write_b16 v238, v32 offset:17408
	v_bfe_u32 v32, v32, 8, 8
	v_lshl_add_u32 v32, v32, 2, v218
	v_mfma_f32_32x32x16_f16 v[0:15], v[104:107], v[156:159], v[0:15]
	ds_add_u32 v32, v227
	s_cbranch_scc1 .LBB0_450
	s_nop 1
	v_max_f32_e32 v16, 0, v16
	v_max_f32_e32 v17, 0, v17
	v_fma_f32 v16, v76, v16, 0
	v_fmac_f32_e32 v16, v77, v17
	v_max_f32_e32 v17, 0, v18
	v_fmac_f32_e32 v16, v78, v17
	v_max_f32_e32 v17, 0, v19
	v_fmac_f32_e32 v16, v79, v17
	v_max_f32_e32 v17, 0, v20
	v_fmac_f32_e32 v16, v80, v17
	v_max_f32_e32 v17, 0, v21
	v_fmac_f32_e32 v16, v81, v17
	v_max_f32_e32 v17, 0, v22
	v_fmac_f32_e32 v16, v82, v17
	v_max_f32_e32 v17, 0, v23
	v_fmac_f32_e32 v16, v83, v17
	v_fmamk_f32 v16, v16, 0x45800000, v226
	v_cvt_i32_f32_e32 v16, v16
	v_add_u32_e32 v17, 0x300, v239
	v_cmp_le_i32_e32 vcc, v17, v234
	v_add_u32_e32 v18, 0xffff0600, v238
	v_med3_i32 v16, v16, 1, s62
	v_cndmask_b32_e32 v16, 0, v16, vcc
	ds_write_b16 v18, v16
	v_max_f32_e32 v18, 0, v24
	v_max_f32_e32 v19, 0, v25
	v_fma_f32 v18, v84, v18, 0
	v_fmac_f32_e32 v18, v85, v19
	v_max_f32_e32 v19, 0, v26
	v_fmac_f32_e32 v18, v86, v19
	v_max_f32_e32 v19, 0, v27
	v_fmac_f32_e32 v18, v87, v19
	v_max_f32_e32 v19, 0, v28
	v_max_f32_e32 v0, 0, v0
	v_fmac_f32_e32 v18, v88, v19
	v_max_f32_e32 v19, 0, v29
	v_max_f32_e32 v1, 0, v1
	v_fma_f32 v0, v108, v0, 0
	v_fmac_f32_e32 v18, v89, v19
	v_max_f32_e32 v19, 0, v30
	v_fmac_f32_e32 v0, v109, v1
	v_max_f32_e32 v1, 0, v2
	v_fmac_f32_e32 v18, v90, v19
	v_max_f32_e32 v19, 0, v31
	v_fmac_f32_e32 v0, v110, v1
	v_max_f32_e32 v1, 0, v3
	v_fmac_f32_e32 v18, v91, v19
	v_fmac_f32_e32 v0, v111, v1
	v_max_f32_e32 v1, 0, v4
	v_fmamk_f32 v18, v18, 0x45800000, v226
	v_cvt_i32_f32_e32 v18, v18
	v_fmac_f32_e32 v0, v112, v1
	v_max_f32_e32 v1, 0, v5
	v_bfe_u32 v16, v16, 8, 8
	v_fmac_f32_e32 v0, v113, v1
	v_max_f32_e32 v1, 0, v6
	v_lshl_add_u32 v16, v16, 2, v212
	ds_add_u32 v16, v227
	v_med3_i32 v16, v18, 1, s62
	v_cmp_le_i32_e32 vcc, v17, v235
	v_fmac_f32_e32 v0, v114, v1
	v_max_f32_e32 v1, 0, v7
	v_cndmask_b32_e32 v16, 0, v16, vcc
	v_add_u32_e32 v18, 0xffff4600, v238
	v_fmac_f32_e32 v0, v115, v1
	v_bfe_u32 v1, v16, 8, 8
	ds_write_b16 v18, v16
	v_lshl_add_u32 v1, v1, 2, v214
	ds_add_u32 v1, v227
	v_max_f32_e32 v1, 0, v8
	v_max_f32_e32 v2, 0, v9
	v_fma_f32 v1, v116, v1, 0
	v_fmac_f32_e32 v1, v117, v2
	v_max_f32_e32 v2, 0, v10
	v_fmac_f32_e32 v1, v118, v2
	v_max_f32_e32 v2, 0, v11
	v_fmac_f32_e32 v1, v119, v2
	v_max_f32_e32 v2, 0, v12
	v_fmac_f32_e32 v1, v120, v2
	v_max_f32_e32 v2, 0, v13
	v_fmac_f32_e32 v1, v121, v2
	v_max_f32_e32 v2, 0, v14
	v_fmamk_f32 v0, v0, 0x45800000, v226
	v_cvt_i32_f32_e32 v0, v0
	v_fmac_f32_e32 v1, v122, v2
	v_max_f32_e32 v2, 0, v15
	v_fmac_f32_e32 v1, v123, v2
	v_fmamk_f32 v1, v1, 0x45800000, v226
	v_med3_i32 v0, v0, 1, s62
	v_cmp_le_i32_e32 vcc, v17, v236
	v_cvt_i32_f32_e32 v1, v1
	s_nop 0
	v_cndmask_b32_e32 v0, 0, v0, vcc
	ds_write_b16 v238, v0 offset:1536
	v_bfe_u32 v0, v0, 8, 8
	v_lshl_add_u32 v0, v0, 2, v216
	ds_add_u32 v0, v227
	v_med3_i32 v0, v1, 1, s62
	v_cmp_le_i32_e32 vcc, v17, v237
	s_nop 1
	v_cndmask_b32_e32 v0, 0, v0, vcc
	ds_write_b16 v238, v0 offset:17920
	v_bfe_u32 v0, v0, 8, 8
	v_lshl_add_u32 v0, v0, 2, v218
	ds_add_u32 v0, v227
	s_branch .LBB0_450
